# v46 + P1 job_shw weight loads software-pipelined one iteration ahead through a staging register set
# baseline (speedup 1.0000x reference)
.LBB0_200:
	s_or_b64 exec, exec, s[38:39]
	s_and_b64 s[34:35], exec, s[34:35]
	s_cselect_b32 s34, 0, s65
	s_sub_i32 s34, s64, s34
	v_and_b32_e32 v8, 63, v10
	s_lshl_b32 s34, s34, 6
	v_ashrrev_i32_e32 v11, 6, v10
	v_or_b32_e32 v2, s34, v8
	v_lshlrev_b32_e32 v0, 7, v11
	v_ashrrev_i32_e32 v3, 31, v2
	s_lshl_b64 s[38:39], s[26:27], 1
	v_ashrrev_i32_e32 v1, 31, v0
	v_lshlrev_b64 v[2:3], 11, v[2:3]
	s_add_u32 s36, s36, s38
	v_lshl_add_u64 v[0:1], v[0:1], 1, v[2:3]
	s_addc_u32 s37, s37, s39
	v_lshl_add_u64 v[0:1], s[36:37], 0, v[0:1]
	v_mov_b32_e32 v14, 0
	s_mov_b32 s7, 0
	v_lshlrev_b32_e32 v22, 9, v11
	v_lshl_add_u64 v[12:13], v[0:1], 0, 16
	v_mov_b32_e32 v15, v14
	v_mov_b32_e32 v16, v14
	v_mov_b32_e32 v17, v14
	v_mov_b32_e32 v18, v14
	v_mov_b32_e32 v19, v14
	v_mov_b32_e32 v20, v14
	v_mov_b32_e32 v21, v14
	v_mov_b32_e32 v23, v14
	s_waitcnt lgkmcnt(0)
	s_barrier
	global_load_dwordx4 v[184:187], v[12:13], off
	global_load_dwordx4 v[188:191], v[12:13], off offset:-16
.LBB0_201:
	v_add_u32_e32 v136, s7, v22
	ds_read_b128 v[24:27], v136 offset:32768
	ds_read_b128 v[28:31], v136 offset:32784
	ds_read_b128 v[32:35], v136
	ds_read_b128 v[36:39], v136 offset:16
	ds_read_b128 v[40:43], v136 offset:32
	ds_read_b128 v[44:47], v136 offset:48
	ds_read_b128 v[48:51], v136 offset:4096
	ds_read_b128 v[52:55], v136 offset:4112
	ds_read_b128 v[56:59], v136 offset:8192
	ds_read_b128 v[60:63], v136 offset:8208
	ds_read_b128 v[64:67], v136 offset:12288
	ds_read_b128 v[68:71], v136 offset:12304
	ds_read_b128 v[72:75], v136 offset:16384
	ds_read_b128 v[76:79], v136 offset:16400
	ds_read_b128 v[80:83], v136 offset:20480
	ds_read_b128 v[84:87], v136 offset:20496
	ds_read_b128 v[88:91], v136 offset:24576
	ds_read_b128 v[92:95], v136 offset:24592
	ds_read_b128 v[96:99], v136 offset:28672
	ds_read_b128 v[100:103], v136 offset:28688
	ds_read_b128 v[104:107], v136 offset:32800
	ds_read_b128 v[108:111], v136 offset:32816
	ds_read_b128 v[112:115], v136 offset:4128
	ds_read_b128 v[116:119], v136 offset:4144
	ds_read_b128 v[120:123], v136 offset:8224
	ds_read_b128 v[124:127], v136 offset:8240
	ds_read_b128 v[128:131], v136 offset:12320
	ds_read_b128 v[132:135], v136 offset:12336
	ds_read_b128 v[140:143], v136 offset:16416
	ds_read_b128 v[144:147], v136 offset:16432
	ds_read_b128 v[148:151], v136 offset:20512
	ds_read_b128 v[156:159], v136 offset:20528
	ds_read_b128 v[160:163], v136 offset:24608
	ds_read_b128 v[164:167], v136 offset:24624
	ds_read_b128 v[168:171], v136 offset:28704
	ds_read_b128 v[172:175], v136 offset:28720
	s_waitcnt lgkmcnt(14)
	v_mov_b32_e32 v136, v32
	v_mov_b32_e32 v137, v48
	v_mov_b32_e32 v48, v33
	v_mov_b32_e32 v32, v34
	v_mov_b32_e32 v33, v50
	v_mov_b32_e32 v50, v35
	v_mov_b32_e32 v34, v36
	v_mov_b32_e32 v35, v52
	v_mov_b32_e32 v52, v37
	v_mov_b32_e32 v36, v38
	v_mov_b32_e32 v37, v54
	v_mov_b32_e32 v54, v39
	v_mov_b32_e32 v38, v56
	v_mov_b32_e32 v39, v64
	v_mov_b32_e32 v64, v57
	v_mov_b32_e32 v56, v58
	v_mov_b32_e32 v57, v66
	v_mov_b32_e32 v66, v59
	v_mov_b32_e32 v58, v60
	v_mov_b32_e32 v59, v68
	v_mov_b32_e32 v68, v61
	v_mov_b32_e32 v60, v62
	v_mov_b32_e32 v61, v70
	v_mov_b32_e32 v70, v63
	v_mov_b32_e32 v62, v72
	v_mov_b32_e32 v63, v80
	v_mov_b32_e32 v80, v73
	v_mov_b32_e32 v72, v74
	v_mov_b32_e32 v73, v82
	v_mov_b32_e32 v82, v75
	v_mov_b32_e32 v74, v76
	v_mov_b32_e32 v75, v84
	v_mov_b32_e32 v84, v77
	v_mov_b32_e32 v76, v78
	v_mov_b32_e32 v77, v86
	v_mov_b32_e32 v86, v79
	v_mov_b32_e32 v78, v88
	v_mov_b32_e32 v79, v96
	v_mov_b32_e32 v96, v89
	v_mov_b32_e32 v88, v90
	v_mov_b32_e32 v89, v98
	v_mov_b32_e32 v98, v91
	v_mov_b32_e32 v90, v92
	v_mov_b32_e32 v91, v100
	v_mov_b32_e32 v100, v93
	v_mov_b32_e32 v92, v94
	v_mov_b32_e32 v93, v102
	v_mov_b32_e32 v102, v95
	v_mov_b32_e32 v94, v40
	s_waitcnt lgkmcnt(13)
	v_mov_b32_e32 v95, v112
	v_mov_b32_e32 v112, v41
	v_mov_b32_e32 v40, v42
	v_mov_b32_e32 v41, v114
	v_mov_b32_e32 v114, v43
	v_mov_b32_e32 v42, v44
	s_waitcnt lgkmcnt(12)
	v_mov_b32_e32 v43, v116
	v_mov_b32_e32 v116, v45
	v_mov_b32_e32 v44, v46
	v_mov_b32_e32 v45, v118
	v_mov_b32_e32 v118, v47
	s_waitcnt lgkmcnt(11)
	v_mov_b32_e32 v46, v120
	s_waitcnt lgkmcnt(9)
	v_mov_b32_e32 v47, v128
	v_mov_b32_e32 v128, v121
	v_mov_b32_e32 v120, v122
	v_mov_b32_e32 v121, v130
	v_mov_b32_e32 v130, v123
	v_mov_b32_e32 v122, v124
	s_waitcnt lgkmcnt(8)
	v_mov_b32_e32 v123, v132
	v_mov_b32_e32 v132, v125
	v_mov_b32_e32 v124, v126
	v_mov_b32_e32 v125, v134
	v_mov_b32_e32 v134, v127
	s_waitcnt lgkmcnt(7)
	v_mov_b32_e32 v126, v140
	s_waitcnt lgkmcnt(5)
	v_mov_b32_e32 v127, v148
	v_mov_b32_e32 v148, v141
	v_mov_b32_e32 v140, v142
	v_mov_b32_e32 v141, v150
	v_mov_b32_e32 v150, v143
	v_mov_b32_e32 v142, v144
	s_waitcnt lgkmcnt(4)
	v_mov_b32_e32 v143, v156
	v_mov_b32_e32 v156, v145
	v_mov_b32_e32 v144, v146
	v_mov_b32_e32 v145, v158
	v_mov_b32_e32 v158, v147
	s_waitcnt lgkmcnt(3)
	v_mov_b32_e32 v146, v160
	s_waitcnt lgkmcnt(1)
	v_mov_b32_e32 v147, v168
	v_mov_b32_e32 v168, v161
	v_mov_b32_e32 v160, v164
	s_waitcnt lgkmcnt(0)
	v_mov_b32_e32 v161, v172
	v_mov_b32_e32 v172, v165
	s_waitcnt vmcnt(0)
	v_mov_b32_e32 v0, v184
	v_mov_b32_e32 v1, v185
	v_mov_b32_e32 v2, v186
	v_mov_b32_e32 v3, v187
	v_mov_b32_e32 v4, v188
	v_mov_b32_e32 v5, v189
	v_mov_b32_e32 v6, v190
	v_mov_b32_e32 v7, v191
	global_load_dwordx4 v[184:187], v[12:13], off offset:32
	global_load_dwordx4 v[188:191], v[12:13], off offset:16
	v_lshlrev_b32_e32 v164, 16, v4
	v_and_b32_e32 v165, 0xffff0000, v4
	v_pk_mul_f32 v[24:25], v[24:25], v[164:165]
	v_lshlrev_b32_e32 v4, 16, v5
	v_and_b32_e32 v5, 0xffff0000, v5
	v_pk_fma_f32 v[14:15], v[136:137], v[164:165], v[14:15] op_sel_hi:[1,0,1]
	v_pk_fma_f32 v[16:17], v[38:39], v[164:165], v[16:17] op_sel_hi:[1,0,1]
	v_pk_fma_f32 v[18:19], v[62:63], v[164:165], v[18:19] op_sel_hi:[1,0,1]
	v_pk_fma_f32 v[20:21], v[78:79], v[164:165], v[20:21] op_sel_hi:[1,0,1]
	v_add_f32_e32 v23, v23, v24
	v_pk_mul_f32 v[26:27], v[26:27], v[4:5]
	v_pk_fma_f32 v[14:15], v[48:49], v[164:165], v[14:15] op_sel:[0,1,0]
	v_pk_fma_f32 v[16:17], v[64:65], v[164:165], v[16:17] op_sel:[0,1,0]
	v_pk_fma_f32 v[18:19], v[80:81], v[164:165], v[18:19] op_sel:[0,1,0]
	v_pk_fma_f32 v[20:21], v[96:97], v[164:165], v[20:21] op_sel:[0,1,0]
	v_add_f32_e32 v23, v23, v25
	v_mov_b32_e32 v152, v162
	v_mov_b32_e32 v153, v170
	v_mov_b32_e32 v170, v163
	v_mov_b32_e32 v162, v166
	v_mov_b32_e32 v163, v174
	v_mov_b32_e32 v174, v167
	v_lshlrev_b32_e32 v166, 16, v6
	v_and_b32_e32 v167, 0xffff0000, v6
	v_pk_fma_f32 v[14:15], v[32:33], v[4:5], v[14:15] op_sel_hi:[1,0,1]
	v_pk_fma_f32 v[16:17], v[56:57], v[4:5], v[16:17] op_sel_hi:[1,0,1]
	v_pk_fma_f32 v[18:19], v[72:73], v[4:5], v[18:19] op_sel_hi:[1,0,1]
	v_pk_fma_f32 v[20:21], v[88:89], v[4:5], v[20:21] op_sel_hi:[1,0,1]
	v_add_f32_e32 v23, v23, v26
	v_pk_mul_f32 v[28:29], v[28:29], v[166:167]
	v_pk_fma_f32 v[14:15], v[50:51], v[4:5], v[14:15] op_sel:[0,1,0]
	v_pk_fma_f32 v[16:17], v[66:67], v[4:5], v[16:17] op_sel:[0,1,0]
	v_pk_fma_f32 v[18:19], v[82:83], v[4:5], v[18:19] op_sel:[0,1,0]
	v_pk_fma_f32 v[4:5], v[98:99], v[4:5], v[20:21] op_sel:[0,1,0]
	v_add_f32_e32 v20, v23, v27
	v_lshlrev_b32_e32 v6, 16, v7
	v_and_b32_e32 v7, 0xffff0000, v7
	v_pk_fma_f32 v[14:15], v[34:35], v[166:167], v[14:15] op_sel_hi:[1,0,1]
	v_pk_fma_f32 v[16:17], v[58:59], v[166:167], v[16:17] op_sel_hi:[1,0,1]
	v_pk_fma_f32 v[18:19], v[74:75], v[166:167], v[18:19] op_sel_hi:[1,0,1]
	v_pk_fma_f32 v[4:5], v[90:91], v[166:167], v[4:5] op_sel_hi:[1,0,1]
	v_add_f32_e32 v20, v20, v28
	v_pk_mul_f32 v[30:31], v[30:31], v[6:7]
	v_pk_fma_f32 v[14:15], v[52:53], v[166:167], v[14:15] op_sel:[0,1,0]
	v_pk_fma_f32 v[16:17], v[68:69], v[166:167], v[16:17] op_sel:[0,1,0]
	v_pk_fma_f32 v[18:19], v[84:85], v[166:167], v[18:19] op_sel:[0,1,0]
	v_pk_fma_f32 v[4:5], v[100:101], v[166:167], v[4:5] op_sel:[0,1,0]
	v_add_f32_e32 v20, v20, v29
	v_lshlrev_b32_e32 v176, 16, v0
	v_and_b32_e32 v177, 0xffff0000, v0
	v_pk_fma_f32 v[14:15], v[36:37], v[6:7], v[14:15] op_sel_hi:[1,0,1]
	v_pk_fma_f32 v[16:17], v[60:61], v[6:7], v[16:17] op_sel_hi:[1,0,1]
	v_pk_fma_f32 v[18:19], v[76:77], v[6:7], v[18:19] op_sel_hi:[1,0,1]
	v_pk_fma_f32 v[4:5], v[92:93], v[6:7], v[4:5] op_sel_hi:[1,0,1]
	v_add_f32_e32 v20, v20, v30
	v_pk_mul_f32 v[38:39], v[104:105], v[176:177]
	v_pk_fma_f32 v[14:15], v[54:55], v[6:7], v[14:15] op_sel:[0,1,0]
	v_pk_fma_f32 v[16:17], v[70:71], v[6:7], v[16:17] op_sel:[0,1,0]
	v_pk_fma_f32 v[18:19], v[86:87], v[6:7], v[18:19] op_sel:[0,1,0]
	v_pk_fma_f32 v[4:5], v[102:103], v[6:7], v[4:5] op_sel:[0,1,0]
	v_add_f32_e32 v20, v20, v31
	v_lshlrev_b32_e32 v0, 16, v1
	v_and_b32_e32 v1, 0xffff0000, v1
	v_pk_fma_f32 v[6:7], v[94:95], v[176:177], v[14:15] op_sel_hi:[1,0,1]
	v_pk_fma_f32 v[14:15], v[46:47], v[176:177], v[16:17] op_sel_hi:[1,0,1]
	v_pk_fma_f32 v[16:17], v[126:127], v[176:177], v[18:19] op_sel_hi:[1,0,1]
	v_pk_fma_f32 v[4:5], v[146:147], v[176:177], v[4:5] op_sel_hi:[1,0,1]
	v_add_f32_e32 v18, v20, v38
	v_pk_mul_f32 v[62:63], v[106:107], v[0:1]
	v_pk_fma_f32 v[6:7], v[112:113], v[176:177], v[6:7] op_sel:[0,1,0]
	v_pk_fma_f32 v[14:15], v[128:129], v[176:177], v[14:15] op_sel:[0,1,0]
	v_pk_fma_f32 v[16:17], v[148:149], v[176:177], v[16:17] op_sel:[0,1,0]
	v_pk_fma_f32 v[4:5], v[168:169], v[176:177], v[4:5] op_sel:[0,1,0]
	v_add_f32_e32 v18, v18, v39
	v_lshlrev_b32_e32 v178, 16, v2
	v_and_b32_e32 v179, 0xffff0000, v2
	v_pk_fma_f32 v[6:7], v[40:41], v[0:1], v[6:7] op_sel_hi:[1,0,1]
	v_pk_fma_f32 v[14:15], v[120:121], v[0:1], v[14:15] op_sel_hi:[1,0,1]
	v_pk_fma_f32 v[16:17], v[140:141], v[0:1], v[16:17] op_sel_hi:[1,0,1]
	v_pk_fma_f32 v[4:5], v[152:153], v[0:1], v[4:5] op_sel_hi:[1,0,1]
	v_add_f32_e32 v18, v18, v62
	v_pk_mul_f32 v[78:79], v[108:109], v[178:179]
	v_pk_fma_f32 v[6:7], v[114:115], v[0:1], v[6:7] op_sel:[0,1,0]
	v_pk_fma_f32 v[14:15], v[130:131], v[0:1], v[14:15] op_sel:[0,1,0]
	v_pk_fma_f32 v[16:17], v[150:151], v[0:1], v[16:17] op_sel:[0,1,0]
	v_pk_fma_f32 v[0:1], v[170:171], v[0:1], v[4:5] op_sel:[0,1,0]
	v_add_f32_e32 v18, v18, v63
	v_lshlrev_b32_e32 v2, 16, v3
	v_and_b32_e32 v3, 0xffff0000, v3
	v_pk_fma_f32 v[4:5], v[42:43], v[178:179], v[6:7] op_sel_hi:[1,0,1]
	v_pk_fma_f32 v[6:7], v[122:123], v[178:179], v[14:15] op_sel_hi:[1,0,1]
	v_pk_fma_f32 v[14:15], v[142:143], v[178:179], v[16:17] op_sel_hi:[1,0,1]
	v_pk_fma_f32 v[0:1], v[160:161], v[178:179], v[0:1] op_sel_hi:[1,0,1]
	v_add_f32_e32 v16, v18, v78
	v_pk_mul_f32 v[104:105], v[110:111], v[2:3]
	v_pk_fma_f32 v[4:5], v[116:117], v[178:179], v[4:5] op_sel:[0,1,0]
	v_pk_fma_f32 v[6:7], v[132:133], v[178:179], v[6:7] op_sel:[0,1,0]
	v_pk_fma_f32 v[14:15], v[156:157], v[178:179], v[14:15] op_sel:[0,1,0]
	v_pk_fma_f32 v[0:1], v[172:173], v[178:179], v[0:1] op_sel:[0,1,0]
	v_add_f32_e32 v16, v16, v79
	s_add_i32 s7, s7, 64
	v_pk_fma_f32 v[4:5], v[44:45], v[2:3], v[4:5] op_sel_hi:[1,0,1]
	v_pk_fma_f32 v[6:7], v[124:125], v[2:3], v[6:7] op_sel_hi:[1,0,1]
	v_pk_fma_f32 v[18:19], v[144:145], v[2:3], v[14:15] op_sel_hi:[1,0,1]
	v_pk_fma_f32 v[0:1], v[162:163], v[2:3], v[0:1] op_sel_hi:[1,0,1]
	v_add_f32_e32 v23, v16, v104
	v_lshl_add_u64 v[12:13], v[12:13], 0, 32
	s_cmpk_eq_i32 s7, 0x200
	v_pk_fma_f32 v[14:15], v[118:119], v[2:3], v[4:5] op_sel:[0,1,0]
	v_pk_fma_f32 v[16:17], v[134:135], v[2:3], v[6:7] op_sel:[0,1,0]
	v_pk_fma_f32 v[18:19], v[158:159], v[2:3], v[18:19] op_sel:[0,1,0]
	v_pk_fma_f32 v[20:21], v[174:175], v[2:3], v[0:1] op_sel:[0,1,0]
	v_add_f32_e32 v23, v23, v105
	s_cbranch_scc0 .LBB0_201
	v_lshlrev_b32_e32 v8, 2, v8
	v_mul_lo_u32 v0, v11, s58
	v_or_b32_e32 v0, v8, v0
	v_cmp_gt_i32_e32 vcc, s59, v10
	s_barrier
	ds_write2st64_b32 v0, v14, v15 offset1:1
	ds_write2st64_b32 v0, v16, v17 offset0:2 offset1:3
	ds_write2st64_b32 v0, v18, v19 offset0:4 offset1:5
	ds_write2st64_b32 v0, v20, v21 offset0:6 offset1:7
	ds_write_b32 v0, v23 offset:2048
	s_waitcnt lgkmcnt(0)
	s_barrier
	s_and_saveexec_b64 s[36:37], vcc
	s_cbranch_execz .LBB0_167
	s_add_u32 s7, s10, s30
	s_mul_i32 s30, s63, s62
	s_addc_u32 s26, s11, s31
	s_lshl_b32 s30, s30, 2
	s_add_u32 s7, s7, s30
	s_addc_u32 s26, s26, 0
	s_ashr_i32 s35, s34, 31
	s_lshl_b64 s[30:31], s[34:35], 2
	v_max_i32_e32 v2, 64, v10
	s_add_u32 s30, s7, s30
	v_sub_u32_e32 v2, v2, v10
	s_addc_u32 s31, s26, s31
	v_add_u32_e32 v2, 0x1ff, v2
	v_lshl_add_u64 v[0:1], s[30:31], 0, v[8:9]
	v_cmp_lt_u32_e32 vcc, s55, v2
	s_mov_b64 s[34:35], -1
	s_and_saveexec_b64 s[30:31], vcc
	s_cbranch_execz .LBB0_211
	v_lshrrev_b32_e32 v4, 9, v2
	v_add_u32_e32 v11, 0x200, v10
	v_add_u32_e32 v5, -1, v4
	v_cmp_lt_u32_e32 vcc, 1, v5
	v_mov_b64_e32 v[2:3], v[10:11]
	s_and_saveexec_b64 s[34:35], vcc
	s_cbranch_execz .LBB0_208
	v_lshrrev_b32_e32 v2, 1, v5
	v_add_u32_e32 v2, 1, v2
	v_and_b32_e32 v6, -2, v2
	s_mov_b64 s[38:39], 0
	v_mov_b64_e32 v[2:3], v[10:11]
